# mLSTM chain: next-chunk prefetch loads go straight to their final registers (no in-loop vmcnt waits for register shuffles); qc/qc2 MFMA chains and VgT scaling with LDS reads issued ahead
# speedup vs baseline: 1.0555x; 1.0435x over previous
; __device__ __forceinline__ void mlstm_task(const Ctx& c, int p, int l, int q, int h, int slab) {
;     ...
;         if (ck + 1 < nch) ML_PREFETCH(rbase + 64);
.LBB0_1615:
	s_or_b64 exec, exec, s[68:69]
	s_cmpk_gt_u32 s75, 0x7e
	s_waitcnt lgkmcnt(0)
	s_barrier
	s_cbranch_scc1 .LBB0_1629
	s_ashr_i32 s81, s80, 31
	s_lshl_b64 s[68:69], s[80:81], 13
	v_lshl_add_u64 v[0:1], v[92:93], 0, s[68:69]
	global_load_dwordx4 v[36:39], v[0:1], off
	v_mov_b64_e32 v[40:41], v[32:33]
	v_mov_b64_e32 v[42:43], v[34:35]
	v_mov_b64_e32 v[44:45], v[32:33]
	v_mov_b64_e32 v[46:47], v[34:35]
	v_mov_b64_e32 v[52:53], v[32:33]
	v_mov_b64_e32 v[54:55], v[34:35]
	v_mov_b64_e32 v[64:65], v[32:33]
	v_mov_b64_e32 v[66:67], v[34:35]
	v_mov_b64_e32 v[14:15], v[32:33]
	v_mov_b64_e32 v[16:17], v[34:35]
	v_mov_b64_e32 v[18:19], v[32:33]
	v_mov_b64_e32 v[20:21], v[34:35]
	v_mov_b64_e32 v[22:23], v[32:33]
	v_mov_b64_e32 v[24:25], v[34:35]
	v_mov_b64_e32 v[26:27], v[32:33]
	v_mov_b64_e32 v[28:29], v[34:35]
	s_and_saveexec_b64 s[68:69], s[4:5]
	s_cbranch_execz .Lml_pf1
	v_add_u32_e32 v1, s96, v187
	v_mov_b64_e32 v[2:3], s[72:73]
	v_mad_i64_i32 v[2:3], s[86:87], v1, s33, v[2:3]
	s_lshl_b32 s90, s88, 1
	v_lshl_add_u64 v[2:3], v[2:3], 0, s[90:91]
	v_lshl_add_u64 v[0:1], v[2:3], 0, v[30:31]
	v_add_co_u32_e32 v2, vcc, 0x1000, v0
	s_nop 1
	v_addc_co_u32_e32 v3, vcc, 0, v1, vcc
	global_load_dwordx4 v[14:17], v[0:1], off offset:2048
	global_load_dwordx4 v[40:43], v[2:3], off
.Lml_pf1:
	s_or_b64 exec, exec, s[68:69]
	s_and_saveexec_b64 s[68:69], s[6:7]
	s_cbranch_execz .Lml_pf2
	v_add_u32_e32 v5, s96, v188
	v_mov_b64_e32 v[6:7], s[72:73]
	v_mad_i64_i32 v[6:7], s[86:87], v5, s33, v[6:7]
	s_lshl_b32 s90, s88, 1
	v_lshl_add_u64 v[6:7], v[6:7], 0, s[90:91]
	v_lshl_add_u64 v[4:5], v[6:7], 0, v[30:31]
	v_add_co_u32_e32 v6, vcc, 0x1000, v4
	s_nop 1
	v_addc_co_u32_e32 v7, vcc, 0, v5, vcc
	global_load_dwordx4 v[18:21], v[4:5], off offset:2048
	global_load_dwordx4 v[44:47], v[6:7], off
.Lml_pf2:
	s_or_b64 exec, exec, s[68:69]
	s_and_saveexec_b64 s[68:69], s[8:9]
	s_cbranch_execz .Lml_pf3
	v_add_u32_e32 v9, s96, v189
	v_mov_b64_e32 v[10:11], s[72:73]
	v_mad_i64_i32 v[10:11], s[86:87], v9, s33, v[10:11]
	s_lshl_b32 s90, s88, 1
	v_lshl_add_u64 v[10:11], v[10:11], 0, s[90:91]
	v_lshl_add_u64 v[8:9], v[10:11], 0, v[30:31]
	v_add_co_u32_e32 v10, vcc, 0x1000, v8
	s_nop 1
	v_addc_co_u32_e32 v11, vcc, 0, v9, vcc
	global_load_dwordx4 v[22:25], v[8:9], off offset:2048
	global_load_dwordx4 v[52:55], v[10:11], off
.Lml_pf3:
	s_or_b64 exec, exec, s[68:69]
	s_and_saveexec_b64 s[68:69], s[10:11]
	s_cbranch_execz .Lml_pf4
	v_add_u32_e32 v85, s96, v190
	v_mov_b64_e32 v[86:87], s[72:73]
	v_mad_i64_i32 v[86:87], s[86:87], v85, s33, v[86:87]
	s_lshl_b32 s90, s88, 1
	v_lshl_add_u64 v[86:87], v[86:87], 0, s[90:91]
	v_lshl_add_u64 v[84:85], v[86:87], 0, v[30:31]
	v_add_co_u32_e32 v86, vcc, 0x1000, v84
	s_nop 1
	v_addc_co_u32_e32 v87, vcc, 0, v85, vcc
	global_load_dwordx4 v[26:29], v[84:85], off offset:2048
	global_load_dwordx4 v[64:67], v[86:87], off
.Lml_pf4:
	s_or_b64 exec, exec, s[68:69]
.LBB0_1624:
	s_or_b64 exec, exec, s[68:69]
	v_cndmask_b32_e64 v59, v12, v59, s[12:13]
	v_cndmask_b32_e64 v58, v12, v58, s[12:13]
	v_cndmask_b32_e64 v57, v12, v57, s[12:13]
	v_cndmask_b32_e64 v56, v12, v56, s[12:13]
	s_and_saveexec_b64 s[68:69], s[84:85]
	s_cbranch_execz .LBB0_1626
	v_add_u32_e32 v2, s96, v185
	v_mov_b64_e32 v[0:1], s[72:73]
	v_mad_i64_i32 v[0:1], s[86:87], v2, s33, v[0:1]
	s_lshl_b32 s90, s88, 1
	v_lshl_add_u64 v[0:1], v[0:1], 0, s[90:91]
	s_lshl_b32 s90, s92, 1
	v_lshl_add_u64 v[0:1], v[0:1], 0, s[90:91]
	v_mov_b32_e32 v105, v31
	v_lshl_add_u64 v[0:1], v[0:1], 0, v[104:105]
	v_add_co_u32_e32 v0, vcc, 0x1000, v0
	s_nop 1
	v_addc_co_u32_e32 v1, vcc, 0, v1, vcc
	global_load_dwordx4 v[56:59], v[0:1], off offset:2048

; #define LAS __attribute__((address_space(3)))
; __device__ __forceinline__ float bf2f(bf16_t b) { return __uint_as_float(((unsigned)b) << 16); }
; __device__ __forceinline__ bf16_t f2bf(float f) { unsigned u = __float_as_uint(f); u += 0x7FFFu + ((u >> 16) & 1u); return (bf16_t)(u >> 16); }
; __device__ __forceinline__ void mlstm_task(const Ctx& c, int p, int l, int q, int h, int slab) {
;     ...
; #pragma unroll
;         for (int i = 0; i < 2; ++i) {
;             const int idx = tid + 512 * i, dp = idx & 127, so = idx >> 7; unsigned wv[8];
; #pragma unroll
;             for (int e = 0; e < 8; ++e) wv[e] = *(const LAS unsigned*)(Ks + (8 * so + e) * 264 + 2 * dp);
;             u32x4 lo, hi;
;             lo.x = (wv[0] & 0xffffu) | (wv[1] << 16); lo.y = (wv[2] & 0xffffu) | (wv[3] << 16); lo.z = (wv[4] & 0xffffu) | (wv[5] << 16); lo.w = (wv[6] & 0xffffu) | (wv[7] << 16);
;             hi.x = (wv[0] >> 16) | (wv[1] & 0xffff0000u); hi.y = (wv[2] >> 16) | (wv[3] & 0xffff0000u); hi.z = (wv[4] >> 16) | (wv[5] & 0xffff0000u); hi.w = (wv[6] >> 16) | (wv[7] & 0xffff0000u);
;             *(LAS u32x4*)(KT + (2 * dp) * 72 + 8 * so) = lo; *(LAS u32x4*)(KT + (2 * dp + 1) * 72 + 8 * so) = hi;
;         }
; #pragma unroll
;         for (int i = 0; i < 4; ++i) { const int idx = tid + 512 * i, v = idx >> 6, s2 = idx & 63; VgT[v * 72 + s2] = f2bf(bf2f(VT[v * 72 + s2]) * gsrc[s2]); }
;         const int ti = w >> 1;
;         const int vj = w & 1;
;         f32x4 qc = {0.f, 0.f, 0.f, 0.f}, qc2 = {0.f, 0.f, 0.f, 0.f};
;         qc = mma_tile(Qs + 16 * ti * 264, 264, Cs + 16 * vj * 264, 264, 256, qc, lane);
;         if (w < 4) qc2 = mma_tile(Qs + 16 * w * 264, 264, Cs + 32 * 264, 264, 256, qc2, lane);
.LBB0_1629:
	v_add_u32_e32 v0, 0x8400, v192
	ds_read2_b32 v[4:5], v0 offset1:132
	v_add_u32_e32 v0, 0x8800, v192
	ds_read2_b32 v[6:7], v0 offset0:8 offset1:140
	v_add_u32_e32 v0, 0x8c00, v192
	ds_read2_b32 v[8:9], v0 offset0:16 offset1:148
	ds_read_b32 v10, v192 offset:36960
	ds_read_b32 v11, v193 offset:33792
	s_waitcnt lgkmcnt(4)
	v_and_b32_e32 v0, 0xffff, v4
	v_lshrrev_b32_e32 v4, 16, v4
	s_mov_b32 s68, 0xffff0000
	v_lshl_or_b32 v0, v5, 16, v0
	s_waitcnt lgkmcnt(3)
	v_and_b32_e32 v1, 0xffff, v6
	s_waitcnt lgkmcnt(2)
	v_and_b32_e32 v2, 0xffff, v8
	s_waitcnt lgkmcnt(1)
	v_and_b32_e32 v3, 0xffff, v10
	v_and_or_b32 v4, v5, s68, v4
	v_lshrrev_b32_e32 v5, 16, v6
	v_lshl_or_b32 v1, v7, 16, v1
	v_lshl_or_b32 v2, v9, 16, v2
	s_waitcnt lgkmcnt(0)
	v_lshl_or_b32 v3, v11, 16, v3
	v_and_or_b32 v5, v7, s68, v5
	v_lshrrev_b32_e32 v6, 16, v8
	v_lshrrev_b32_e32 v7, 16, v10
	v_and_or_b32 v6, v9, s68, v6
	v_and_or_b32 v7, v11, s68, v7
	ds_write_b128 v99, v[0:3]
	ds_write_b128 v99, v[4:7] offset:144
	v_add_u32_e32 v0, 0x8400, v194
	ds_read2_b32 v[4:5], v0 offset1:132
	v_add_u32_e32 v0, 0x8800, v194
	ds_read2_b32 v[6:7], v0 offset0:8 offset1:140
	v_add_u32_e32 v0, 0x8c00, v194
	ds_read2_b32 v[8:9], v0 offset0:16 offset1:148
	ds_read_b32 v10, v194 offset:36960
	ds_read_b32 v11, v195 offset:33792
	s_waitcnt lgkmcnt(4)
	v_and_b32_e32 v0, 0xffff, v4
	v_lshrrev_b32_e32 v4, 16, v4
	v_lshl_or_b32 v0, v5, 16, v0
	s_waitcnt lgkmcnt(3)
	v_and_b32_e32 v1, 0xffff, v6
	s_waitcnt lgkmcnt(2)
	v_and_b32_e32 v2, 0xffff, v8
	s_waitcnt lgkmcnt(1)
	v_and_b32_e32 v3, 0xffff, v10
	v_and_or_b32 v4, v5, s68, v4
	v_lshrrev_b32_e32 v5, 16, v6
	v_lshl_or_b32 v1, v7, 16, v1
	v_lshl_or_b32 v2, v9, 16, v2
	s_waitcnt lgkmcnt(0)
	v_lshl_or_b32 v3, v11, 16, v3
	v_and_or_b32 v5, v7, s68, v5
	v_lshrrev_b32_e32 v6, 16, v8
	v_lshrrev_b32_e32 v7, 16, v10
	v_and_or_b32 v6, v9, s68, v6
	v_and_or_b32 v7, v11, s68, v7
	ds_write_b128 v101, v[0:3]
	ds_write_b128 v101, v[4:7] offset:144
	ds_read_b32 v0, v119
	ds_read_u16 v1, v103
	ds_read_u16 v2, v133
	ds_read_u16 v3, v135
	ds_read_u16 v5, v145
	s_andn2_b64 vcc, exec, s[82:83]
	s_waitcnt lgkmcnt(3)
	v_lshlrev_b32_e32 v1, 16, v1
	v_mul_f32_e32 v1, v0, v1
	v_bfe_u32 v6, v1, 16, 1
	v_add3_u32 v1, v1, v6, s1
	ds_write_b16_d16_hi v132, v1
	s_waitcnt lgkmcnt(3)
	v_lshlrev_b32_e32 v2, 16, v2
	v_mul_f32_e32 v2, v0, v2
	v_bfe_u32 v6, v2, 16, 1
	v_add3_u32 v2, v2, v6, s1
	ds_write_b16_d16_hi v134, v2
	s_waitcnt lgkmcnt(3)
	v_lshlrev_b32_e32 v3, 16, v3
	v_mul_f32_e32 v3, v0, v3
	v_bfe_u32 v6, v3, 16, 1
	v_add3_u32 v3, v3, v6, s1
	ds_write_b16_d16_hi v144, v3
	s_waitcnt lgkmcnt(3)
	v_lshlrev_b32_e32 v5, 16, v5
	v_mul_f32_e32 v5, v0, v5
	v_bfe_u32 v6, v5, 16, 1
	v_add3_u32 v5, v5, v6, s1
	ds_write_b16_d16_hi v146, v5
	ds_read_b128 v[4:7], v120
	ds_read_b128 v[8:11], v121
	ds_read_b128 v[84:87], v120 offset:64
	ds_read_b128 v[106:109], v121 offset:64
	ds_read_b128 v[110:113], v120 offset:128
	ds_read_b128 v[136:139], v121 offset:128
	ds_read_b128 v[200:203], v120 offset:192
	ds_read_b128 v[204:207], v121 offset:192
	s_waitcnt lgkmcnt(6)
	v_mfma_f32_16x16x32_bf16 v[0:3], v[4:7], v[8:11], 0
	ds_read_b128 v[4:7], v120 offset:256
	ds_read_b128 v[8:11], v121 offset:256
	s_waitcnt lgkmcnt(6)
	v_mfma_f32_16x16x32_bf16 v[0:3], v[84:87], v[106:109], v[0:3]
	ds_read_b128 v[84:87], v120 offset:320
	ds_read_b128 v[106:109], v121 offset:320
	s_waitcnt lgkmcnt(6)
	v_mfma_f32_16x16x32_bf16 v[0:3], v[110:113], v[136:139], v[0:3]
	ds_read_b128 v[110:113], v120 offset:384
	ds_read_b128 v[136:139], v121 offset:384
	s_waitcnt lgkmcnt(6)
	v_mfma_f32_16x16x32_bf16 v[0:3], v[200:203], v[204:207], v[0:3]
	ds_read_b128 v[200:203], v120 offset:448
	ds_read_b128 v[204:207], v121 offset:448
	s_waitcnt lgkmcnt(6)
	v_mfma_f32_16x16x32_bf16 v[0:3], v[4:7], v[8:11], v[0:3]
	s_waitcnt lgkmcnt(4)
	v_mfma_f32_16x16x32_bf16 v[0:3], v[84:87], v[106:109], v[0:3]
	s_waitcnt lgkmcnt(2)
	v_mfma_f32_16x16x32_bf16 v[0:3], v[110:113], v[136:139], v[0:3]
	s_waitcnt lgkmcnt(0)
	v_mfma_f32_16x16x32_bf16 v[0:3], v[200:203], v[204:207], v[0:3]
	v_cndmask_b32_e64 v4, 0, 1, s[82:83]
	v_mov_b32_e32 v8, 0
	v_cmp_ne_u32_e64 s[68:69], 1, v4
	v_mov_b32_e32 v9, 0
	v_mov_b32_e32 v10, 0
	v_mov_b32_e32 v11, 0
	s_cbranch_vccnz .LBB0_1631
	ds_read_b128 v[84:87], v196
	ds_read_b128 v[106:109], v89
	ds_read_b128 v[110:113], v196 offset:64
	ds_read_b128 v[136:139], v89 offset:64
	ds_read_b128 v[200:203], v196 offset:128
	ds_read_b128 v[204:207], v89 offset:128
	s_waitcnt lgkmcnt(4)
	v_mfma_f32_16x16x32_bf16 v[8:11], v[84:87], v[106:109], 0
	ds_read_b128 v[84:87], v196 offset:192
	ds_read_b128 v[106:109], v89 offset:192
	s_waitcnt lgkmcnt(4)
	v_mfma_f32_16x16x32_bf16 v[8:11], v[110:113], v[136:139], v[8:11]
	ds_read_b128 v[110:113], v196 offset:256
	ds_read_b128 v[136:139], v89 offset:256
	s_waitcnt lgkmcnt(4)
	v_mfma_f32_16x16x32_bf16 v[8:11], v[200:203], v[204:207], v[8:11]
	ds_read_b128 v[200:203], v196 offset:320
	ds_read_b128 v[204:207], v89 offset:320
	s_waitcnt lgkmcnt(4)
	v_mfma_f32_16x16x32_bf16 v[8:11], v[84:87], v[106:109], v[8:11]
	ds_read_b128 v[84:87], v196 offset:384
	ds_read_b128 v[106:109], v89 offset:384
	s_waitcnt lgkmcnt(4)
	v_mfma_f32_16x16x32_bf16 v[8:11], v[110:113], v[136:139], v[8:11]
	ds_read_b128 v[110:113], v196 offset:448
	ds_read_b128 v[136:139], v89 offset:448
	s_waitcnt lgkmcnt(4)
	v_mfma_f32_16x16x32_bf16 v[8:11], v[200:203], v[204:207], v[8:11]
	s_waitcnt lgkmcnt(2)
	v_mfma_f32_16x16x32_bf16 v[8:11], v[84:87], v[106:109], v[8:11]
	s_waitcnt lgkmcnt(0)
	v_mfma_f32_16x16x32_bf16 v[8:11], v[110:113], v[136:139], v[8:11]
